# residual epilogues (out-proj, down): the four residual loads of a row group issued together with counted vmcnt
# baseline (speedup 1.0000x reference)
.LBB0_1164:
	v_lshl_add_u32 v138, s35, 8, v140
	v_lshl_or_b32 v136, s34, 8, v142
	v_ashrrev_i32_e32 v139, 31, v138
	v_ashrrev_i32_e32 v137, 31, v136
	v_lshlrev_b64 v[144:145], 10, v[138:139]
	v_lshl_add_u64 v[148:149], v[144:145], 0, v[136:137]
	v_readlane_b32 s52, v255, 6
	v_lshlrev_b64 v[150:151], 2, v[148:149]
	v_readlane_b32 s53, v255, 7
	v_lshl_add_u64 v[154:155], v[148:149], 1, s[6:7]
	s_nop 0
	v_lshl_add_u64 v[152:153], s[52:53], 0, v[150:151]
	global_load_dwordx4 v[164:167], v[152:153], off
	global_load_dwordx4 v[168:171], v[152:153], off offset:64
	global_load_dwordx4 v[172:175], v[152:153], off offset:512
	global_load_dwordx4 v[176:179], v[152:153], off offset:576
	v_readlane_b32 s52, v254, 45
	v_readlane_b32 s58, v254, 51
	v_readlane_b32 s59, v254, 52
	v_readlane_b32 s53, v254, 46
	s_lshl_b32 s52, s34, 2
	v_lshl_add_u64 v[156:157], s[58:59], 0, v[150:151]
	v_readlane_b32 s54, v254, 47
	v_readlane_b32 s55, v254, 48
	s_ashr_i32 s53, s52, 31
	v_readlane_b32 s56, v254, 49
	v_readlane_b32 s57, v254, 50
	s_waitcnt vmcnt(3) lgkmcnt(0)
	v_mov_b64_e32 v[144:145], v[164:165]
	v_mov_b64_e32 v[146:147], v[166:167]
	v_pk_add_f32 v[128:129], v[128:129], v[146:147]
	v_pk_add_f32 v[126:127], v[126:127], v[144:145]
	v_cvt_pk_bf16_f32 v145, v128, v129
	v_cvt_pk_bf16_f32 v144, v126, v127
	global_store_dwordx4 v[156:157], v[126:129], off
	global_store_dwordx2 v[154:155], v[144:145], off
	s_waitcnt vmcnt(4) lgkmcnt(0)
	v_mov_b64_e32 v[144:145], v[168:169]
	v_mov_b64_e32 v[146:147], v[170:171]
	v_pk_add_f32 v[124:125], v[124:125], v[146:147]
	v_pk_add_f32 v[122:123], v[122:123], v[144:145]
	v_cvt_pk_bf16_f32 v145, v124, v125
	v_cvt_pk_bf16_f32 v144, v122, v123
	global_store_dwordx4 v[156:157], v[122:125], off offset:64
	global_store_dwordx2 v[154:155], v[144:145], off offset:32
	s_waitcnt vmcnt(5) lgkmcnt(0)
	v_mov_b64_e32 v[144:145], v[172:173]
	v_mov_b64_e32 v[146:147], v[174:175]
	v_pk_add_f32 v[146:147], v[120:121], v[146:147]
	v_pk_add_f32 v[144:145], v[118:119], v[144:145]
	v_cvt_pk_bf16_f32 v119, v146, v147
	v_cvt_pk_bf16_f32 v118, v144, v145
	global_store_dwordx4 v[156:157], v[144:147], off offset:512
	global_store_dwordx2 v[154:155], v[118:119], off offset:256
	v_mul_f32_e32 v120, v127, v127
	v_mul_f32_e32 v121, v129, v129
	v_fmac_f32_e32 v120, v126, v126
	v_fmac_f32_e32 v121, v128, v128
	v_add_f32_e32 v120, v120, v121
	v_mul_f32_e32 v121, v123, v123
	v_mul_f32_e32 v123, v125, v125
	v_fmac_f32_e32 v121, v122, v122
	v_fmac_f32_e32 v123, v124, v124
	v_add_f32_e32 v121, v121, v123
	v_add_f32_e32 v120, v120, v121
	v_mul_f32_e32 v121, v145, v145
	v_mul_f32_e32 v122, v147, v147
	v_fmac_f32_e32 v121, v144, v144
	v_fmac_f32_e32 v122, v146, v146
	v_add_f32_e32 v121, v121, v122
	v_and_b32_e32 v119, 64, v197
	v_add_f32_e32 v124, v120, v121
	v_xor_b32_e32 v118, 16, v197
	v_add_u32_e32 v119, 64, v119
	v_cmp_lt_i32_e32 vcc, v118, v119
	s_waitcnt vmcnt(6) lgkmcnt(0)
	v_mov_b64_e32 v[148:149], v[176:177]
	v_mov_b64_e32 v[150:151], v[178:179]
	v_pk_add_f32 v[122:123], v[116:117], v[150:151]
	v_pk_add_f32 v[120:121], v[114:115], v[148:149]
	v_mul_f32_e32 v115, v123, v123
	v_mul_f32_e32 v114, v121, v121
	v_fmac_f32_e32 v114, v120, v120
	v_fmac_f32_e32 v115, v122, v122
	v_cndmask_b32_e32 v118, v197, v118, vcc
	v_add_f32_e32 v114, v114, v115
	v_lshlrev_b32_e32 v118, 2, v118
	v_add_f32_e32 v114, v124, v114
	ds_bpermute_b32 v115, v118, v114
	v_xor_b32_e32 v116, 32, v197
	v_cmp_lt_i32_e32 vcc, v116, v119
	global_store_dwordx4 v[156:157], v[120:123], off offset:576
	s_waitcnt lgkmcnt(0)
	v_add_f32_e32 v114, v114, v115
	v_cndmask_b32_e32 v116, v197, v116, vcc
	v_lshlrev_b32_e32 v116, 2, v116
	ds_bpermute_b32 v115, v116, v114
	v_cvt_pk_bf16_f32 v120, v120, v121
	v_cvt_pk_bf16_f32 v121, v122, v123
	global_store_dwordx2 v[154:155], v[120:121], off offset:288
	s_and_saveexec_b64 s[54:55], s[0:1]
	s_cbranch_execz .LBB0_1166
	v_readlane_b32 s34, v254, 43
	v_lshlrev_b64 v[120:121], 6, v[138:139]
	v_readlane_b32 s35, v254, 44
	v_lshl_add_u64 v[120:121], s[42:43], 0, v[120:121]
	s_mov_b32 s31, s35
	v_lshl_add_u64 v[120:121], s[52:53], 2, v[120:121]
	s_lshl_b32 s34, s64, 2
	v_writelane_b32 v254, s30, 43
	v_lshl_add_u64 v[120:121], v[120:121], 0, s[34:35]
	s_waitcnt lgkmcnt(0)
	v_add_f32_e32 v114, v114, v115
	v_writelane_b32 v254, s31, 44
	global_store_dword v[120:121], v114, off
.LBB0_1166:
	s_or_b64 exec, exec, s[54:55]
	v_or_b32_e32 v114, 16, v138
	s_waitcnt lgkmcnt(0)
	v_ashrrev_i32_e32 v115, 31, v114
	v_lshlrev_b64 v[120:121], 10, v[114:115]
	v_lshl_add_u64 v[124:125], v[120:121], 0, v[136:137]
	v_readlane_b32 s34, v255, 6
	v_lshlrev_b64 v[126:127], 2, v[124:125]
	v_readlane_b32 s35, v255, 7
	v_readlane_b32 s68, v254, 45
	v_readlane_b32 s74, v254, 51
	v_lshl_add_u64 v[128:129], s[34:35], 0, v[126:127]
	global_load_dwordx4 v[164:167], v[128:129], off
	global_load_dwordx4 v[168:171], v[128:129], off offset:64
	global_load_dwordx4 v[172:175], v[128:129], off offset:512
	global_load_dwordx4 v[176:179], v[128:129], off offset:576
	v_readlane_b32 s75, v254, 52
	v_lshl_add_u64 v[124:125], v[124:125], 1, s[6:7]
	v_readlane_b32 s69, v254, 46
	v_lshl_add_u64 v[126:127], s[74:75], 0, v[126:127]
	v_readlane_b32 s70, v254, 47
	v_readlane_b32 s71, v254, 48
	v_readlane_b32 s72, v254, 49
	v_readlane_b32 s73, v254, 50
	s_waitcnt vmcnt(3) lgkmcnt(0)
	v_mov_b64_e32 v[120:121], v[164:165]
	v_mov_b64_e32 v[122:123], v[166:167]
	v_pk_add_f32 v[112:113], v[112:113], v[122:123]
	v_pk_add_f32 v[110:111], v[110:111], v[120:121]
	v_cvt_pk_bf16_f32 v121, v112, v113
	v_cvt_pk_bf16_f32 v120, v110, v111
	global_store_dwordx4 v[126:127], v[110:113], off
	global_store_dwordx2 v[124:125], v[120:121], off
	v_mul_f32_e32 v111, v111, v111
	v_mul_f32_e32 v113, v113, v113
	v_fmac_f32_e32 v111, v110, v110
	v_fmac_f32_e32 v113, v112, v112
	v_add_f32_e32 v110, v111, v113
	s_waitcnt vmcnt(4) lgkmcnt(0)
	v_mov_b64_e32 v[120:121], v[168:169]
	v_mov_b64_e32 v[122:123], v[170:171]
	v_pk_add_f32 v[108:109], v[108:109], v[122:123]
	v_pk_add_f32 v[106:107], v[106:107], v[120:121]
	v_cvt_pk_bf16_f32 v121, v108, v109
	v_cvt_pk_bf16_f32 v120, v106, v107
	global_store_dwordx4 v[126:127], v[106:109], off offset:64
	global_store_dwordx2 v[124:125], v[120:121], off offset:32
	v_mul_f32_e32 v107, v107, v107
	v_mul_f32_e32 v109, v109, v109
	v_fmac_f32_e32 v107, v106, v106
	v_fmac_f32_e32 v109, v108, v108
	v_add_f32_e32 v106, v107, v109
	v_add_f32_e32 v106, v110, v106
	s_waitcnt vmcnt(5) lgkmcnt(0)
	v_mov_b64_e32 v[120:121], v[172:173]
	v_mov_b64_e32 v[122:123], v[174:175]
	v_pk_add_f32 v[104:105], v[104:105], v[122:123]
	v_pk_add_f32 v[102:103], v[102:103], v[120:121]
	v_cvt_pk_bf16_f32 v121, v104, v105
	v_cvt_pk_bf16_f32 v120, v102, v103
	global_store_dwordx4 v[126:127], v[102:105], off offset:512
	global_store_dwordx2 v[124:125], v[120:121], off offset:256
	v_mul_f32_e32 v103, v103, v103
	v_mul_f32_e32 v105, v105, v105
	v_fmac_f32_e32 v103, v102, v102
	v_fmac_f32_e32 v105, v104, v104
	v_add_f32_e32 v102, v103, v105
	v_add_f32_e32 v104, v106, v102
	s_waitcnt vmcnt(6) lgkmcnt(0)
	v_mov_b64_e32 v[120:121], v[176:177]
	v_mov_b64_e32 v[122:123], v[178:179]
	v_pk_add_f32 v[102:103], v[100:101], v[122:123]
	v_pk_add_f32 v[100:101], v[98:99], v[120:121]
	v_mul_f32_e32 v99, v103, v103
	v_mul_f32_e32 v98, v101, v101
	v_fmac_f32_e32 v98, v100, v100
	v_fmac_f32_e32 v99, v102, v102
	v_add_f32_e32 v98, v98, v99
	v_add_f32_e32 v98, v104, v98
	ds_bpermute_b32 v99, v118, v98
	global_store_dwordx4 v[126:127], v[100:103], off offset:576
	s_waitcnt lgkmcnt(0)
	v_add_f32_e32 v98, v98, v99
	ds_bpermute_b32 v99, v116, v98
	v_cvt_pk_bf16_f32 v100, v100, v101
	v_cvt_pk_bf16_f32 v101, v102, v103
	global_store_dwordx2 v[124:125], v[100:101], off offset:288
	s_and_saveexec_b64 s[54:55], s[0:1]
	s_cbranch_execz .LBB0_1168
	v_readlane_b32 s34, v254, 43
	v_lshlrev_b64 v[100:101], 6, v[114:115]
	v_readlane_b32 s35, v254, 44
	v_lshl_add_u64 v[100:101], s[42:43], 0, v[100:101]
	s_mov_b32 s31, s35
	v_lshl_add_u64 v[100:101], s[52:53], 2, v[100:101]
	s_lshl_b32 s34, s64, 2
	v_writelane_b32 v254, s30, 43
	v_lshl_add_u64 v[100:101], v[100:101], 0, s[34:35]
	s_waitcnt lgkmcnt(0)
	v_add_f32_e32 v98, v98, v99
	v_writelane_b32 v254, s31, 44
	global_store_dword v[100:101], v98, off
.LBB0_1168:
	s_or_b64 exec, exec, s[54:55]
	v_or_b32_e32 v98, 32, v138
	s_waitcnt lgkmcnt(0)
	v_ashrrev_i32_e32 v99, 31, v98
	v_lshlrev_b64 v[100:101], 10, v[98:99]
	v_lshl_add_u64 v[104:105], v[100:101], 0, v[136:137]
	v_readlane_b32 s34, v255, 6
	v_lshlrev_b64 v[106:107], 2, v[104:105]
	v_readlane_b32 s35, v255, 7
	v_readlane_b32 s68, v254, 45
	v_readlane_b32 s74, v254, 51
	v_lshl_add_u64 v[108:109], s[34:35], 0, v[106:107]
	global_load_dwordx4 v[164:167], v[108:109], off
	global_load_dwordx4 v[168:171], v[108:109], off offset:64
	global_load_dwordx4 v[172:175], v[108:109], off offset:512
	global_load_dwordx4 v[176:179], v[108:109], off offset:576
	v_readlane_b32 s75, v254, 52
	v_lshl_add_u64 v[104:105], v[104:105], 1, s[6:7]
	v_readlane_b32 s69, v254, 46
	v_lshl_add_u64 v[106:107], s[74:75], 0, v[106:107]
	v_readlane_b32 s70, v254, 47
	v_readlane_b32 s71, v254, 48
	v_readlane_b32 s72, v254, 49
	v_readlane_b32 s73, v254, 50
	s_waitcnt vmcnt(3) lgkmcnt(0)
	v_mov_b64_e32 v[100:101], v[164:165]
	v_mov_b64_e32 v[102:103], v[166:167]
	v_pk_add_f32 v[96:97], v[96:97], v[102:103]
	v_pk_add_f32 v[94:95], v[94:95], v[100:101]
	v_cvt_pk_bf16_f32 v101, v96, v97
	v_cvt_pk_bf16_f32 v100, v94, v95
	global_store_dwordx4 v[106:107], v[94:97], off
	global_store_dwordx2 v[104:105], v[100:101], off
	v_mul_f32_e32 v95, v95, v95
	v_mul_f32_e32 v97, v97, v97
	v_fmac_f32_e32 v95, v94, v94
	v_fmac_f32_e32 v97, v96, v96
	v_add_f32_e32 v94, v95, v97
	s_waitcnt vmcnt(4) lgkmcnt(0)
	v_mov_b64_e32 v[100:101], v[168:169]
	v_mov_b64_e32 v[102:103], v[170:171]
	v_pk_add_f32 v[92:93], v[92:93], v[102:103]
	v_pk_add_f32 v[90:91], v[90:91], v[100:101]
	v_cvt_pk_bf16_f32 v101, v92, v93
	v_cvt_pk_bf16_f32 v100, v90, v91
	global_store_dwordx4 v[106:107], v[90:93], off offset:64
	global_store_dwordx2 v[104:105], v[100:101], off offset:32
	v_mul_f32_e32 v91, v91, v91
	v_mul_f32_e32 v93, v93, v93
	v_fmac_f32_e32 v91, v90, v90
	v_fmac_f32_e32 v93, v92, v92
	v_add_f32_e32 v90, v91, v93
	v_add_f32_e32 v90, v94, v90
	s_waitcnt vmcnt(5) lgkmcnt(0)
	v_mov_b64_e32 v[100:101], v[172:173]
	v_mov_b64_e32 v[102:103], v[174:175]
	v_pk_add_f32 v[88:89], v[88:89], v[102:103]
	v_pk_add_f32 v[86:87], v[86:87], v[100:101]
	v_cvt_pk_bf16_f32 v101, v88, v89
	v_cvt_pk_bf16_f32 v100, v86, v87
	global_store_dwordx4 v[106:107], v[86:89], off offset:512
	global_store_dwordx2 v[104:105], v[100:101], off offset:256
	v_mul_f32_e32 v87, v87, v87
	v_mul_f32_e32 v89, v89, v89
	v_fmac_f32_e32 v87, v86, v86
	v_fmac_f32_e32 v89, v88, v88
	v_add_f32_e32 v86, v87, v89
	v_add_f32_e32 v88, v90, v86
	s_waitcnt vmcnt(6) lgkmcnt(0)
	v_mov_b64_e32 v[100:101], v[176:177]
	v_mov_b64_e32 v[102:103], v[178:179]
	v_pk_add_f32 v[86:87], v[84:85], v[102:103]
	v_pk_add_f32 v[84:85], v[82:83], v[100:101]
	v_mul_f32_e32 v83, v87, v87
	v_mul_f32_e32 v82, v85, v85
	v_fmac_f32_e32 v82, v84, v84
	v_fmac_f32_e32 v83, v86, v86
	v_add_f32_e32 v82, v82, v83
	v_add_f32_e32 v82, v88, v82
	ds_bpermute_b32 v83, v118, v82
	global_store_dwordx4 v[106:107], v[84:87], off offset:576
	s_waitcnt lgkmcnt(0)
	v_add_f32_e32 v82, v82, v83
	ds_bpermute_b32 v83, v116, v82
	v_cvt_pk_bf16_f32 v84, v84, v85
	v_cvt_pk_bf16_f32 v85, v86, v87
	global_store_dwordx2 v[104:105], v[84:85], off offset:288
	s_mov_b64 s[54:55], exec
	v_readlane_b32 s92, v252, 6
	s_and_b64 s[34:35], s[54:55], s[0:1]
	v_readlane_b32 s93, v252, 7
	v_mov_b32_e32 v200, v202
	s_mov_b64 exec, s[34:35]
	s_cbranch_execz .LBB0_1170
	v_readlane_b32 s34, v254, 43
	v_lshlrev_b64 v[84:85], 6, v[98:99]
	v_readlane_b32 s35, v254, 44
	v_lshl_add_u64 v[84:85], s[42:43], 0, v[84:85]
	s_mov_b32 s31, s35
	v_lshl_add_u64 v[84:85], s[52:53], 2, v[84:85]
	s_lshl_b32 s34, s64, 2
	v_writelane_b32 v254, s30, 43
	v_lshl_add_u64 v[84:85], v[84:85], 0, s[34:35]
	s_waitcnt lgkmcnt(0)
	v_add_f32_e32 v82, v82, v83
	v_writelane_b32 v254, s31, 44
	global_store_dword v[84:85], v82, off
.LBB0_1170:
	s_or_b64 exec, exec, s[54:55]
	v_or_b32_e32 v82, 48, v138
	s_waitcnt lgkmcnt(0)
	v_ashrrev_i32_e32 v83, 31, v82
	v_lshlrev_b64 v[84:85], 10, v[82:83]
	v_lshl_add_u64 v[88:89], v[84:85], 0, v[136:137]
	v_readlane_b32 s34, v255, 6
	v_lshlrev_b64 v[90:91], 2, v[88:89]
	v_readlane_b32 s35, v255, 7
	v_readlane_b32 s84, v254, 45
	v_readlane_b32 s90, v254, 51
	v_lshl_add_u64 v[92:93], s[34:35], 0, v[90:91]
	global_load_dwordx4 v[164:167], v[92:93], off
	global_load_dwordx4 v[168:171], v[92:93], off offset:64
	global_load_dwordx4 v[172:175], v[92:93], off offset:512
	global_load_dwordx4 v[176:179], v[92:93], off offset:576
	v_readlane_b32 s91, v254, 52
	v_lshl_add_u64 v[88:89], v[88:89], 1, s[6:7]
	v_readlane_b32 s85, v254, 46
	v_lshl_add_u64 v[90:91], s[90:91], 0, v[90:91]
	v_readlane_b32 s86, v254, 47
	v_readlane_b32 s87, v254, 48
	v_readlane_b32 s88, v254, 49
	v_readlane_b32 s89, v254, 50
	s_waitcnt vmcnt(3) lgkmcnt(0)
	v_mov_b64_e32 v[84:85], v[164:165]
	v_mov_b64_e32 v[86:87], v[166:167]
	v_pk_add_f32 v[80:81], v[80:81], v[86:87]
	v_pk_add_f32 v[78:79], v[78:79], v[84:85]
	v_cvt_pk_bf16_f32 v85, v80, v81
	v_cvt_pk_bf16_f32 v84, v78, v79
	global_store_dwordx4 v[90:91], v[78:81], off
	global_store_dwordx2 v[88:89], v[84:85], off
	v_mul_f32_e32 v79, v79, v79
	v_mul_f32_e32 v81, v81, v81
	v_fmac_f32_e32 v79, v78, v78
	v_fmac_f32_e32 v81, v80, v80
	v_add_f32_e32 v78, v79, v81
	s_waitcnt vmcnt(4) lgkmcnt(0)
	v_mov_b64_e32 v[84:85], v[168:169]
	v_mov_b64_e32 v[86:87], v[170:171]
	v_pk_add_f32 v[76:77], v[76:77], v[86:87]
	v_pk_add_f32 v[74:75], v[74:75], v[84:85]
	v_cvt_pk_bf16_f32 v85, v76, v77
	v_cvt_pk_bf16_f32 v84, v74, v75
	global_store_dwordx4 v[90:91], v[74:77], off offset:64
	global_store_dwordx2 v[88:89], v[84:85], off offset:32
	v_mul_f32_e32 v75, v75, v75
	v_mul_f32_e32 v77, v77, v77
	v_fmac_f32_e32 v75, v74, v74
	v_fmac_f32_e32 v77, v76, v76
	v_add_f32_e32 v74, v75, v77
	v_add_f32_e32 v74, v78, v74
	s_waitcnt vmcnt(5) lgkmcnt(0)
	v_mov_b64_e32 v[84:85], v[172:173]
	v_mov_b64_e32 v[86:87], v[174:175]
	v_pk_add_f32 v[72:73], v[72:73], v[86:87]
	v_pk_add_f32 v[70:71], v[70:71], v[84:85]
	v_cvt_pk_bf16_f32 v85, v72, v73
	v_cvt_pk_bf16_f32 v84, v70, v71
	global_store_dwordx4 v[90:91], v[70:73], off offset:512
	global_store_dwordx2 v[88:89], v[84:85], off offset:256
	v_mul_f32_e32 v71, v71, v71
	v_mul_f32_e32 v73, v73, v73
	v_fmac_f32_e32 v71, v70, v70
	v_fmac_f32_e32 v73, v72, v72
	v_add_f32_e32 v70, v71, v73
	v_add_f32_e32 v72, v74, v70
	s_waitcnt vmcnt(6) lgkmcnt(0)
	v_mov_b64_e32 v[84:85], v[176:177]
	v_mov_b64_e32 v[86:87], v[178:179]
	v_pk_add_f32 v[70:71], v[68:69], v[86:87]
	v_pk_add_f32 v[68:69], v[66:67], v[84:85]
	v_mul_f32_e32 v67, v71, v71
	v_mul_f32_e32 v66, v69, v69
	v_fmac_f32_e32 v66, v68, v68
	v_fmac_f32_e32 v67, v70, v70
	v_add_f32_e32 v66, v66, v67
	v_add_f32_e32 v66, v72, v66
	ds_bpermute_b32 v67, v118, v66
	global_store_dwordx4 v[90:91], v[68:71], off offset:576
	s_waitcnt lgkmcnt(0)
	v_add_f32_e32 v66, v66, v67
	ds_bpermute_b32 v67, v116, v66
	v_cvt_pk_bf16_f32 v68, v68, v69
	v_cvt_pk_bf16_f32 v69, v70, v71
	global_store_dwordx2 v[88:89], v[68:69], off offset:288
	s_and_saveexec_b64 s[54:55], s[0:1]
	s_cbranch_execz .LBB0_1172
	v_readlane_b32 s34, v254, 43
	v_lshlrev_b64 v[68:69], 6, v[82:83]
	v_readlane_b32 s35, v254, 44
	v_lshl_add_u64 v[68:69], s[42:43], 0, v[68:69]
	s_mov_b32 s31, s35
	v_lshl_add_u64 v[68:69], s[52:53], 2, v[68:69]
	s_lshl_b32 s34, s64, 2
	v_writelane_b32 v254, s30, 43
	v_lshl_add_u64 v[68:69], v[68:69], 0, s[34:35]
	s_waitcnt lgkmcnt(0)
	v_add_f32_e32 v66, v66, v67
	v_writelane_b32 v254, s31, 44
	global_store_dword v[68:69], v66, off
.LBB0_1172:
	s_or_b64 exec, exec, s[54:55]
	v_add_u32_e32 v66, 0x80, v138
	s_waitcnt lgkmcnt(0)
	v_ashrrev_i32_e32 v67, 31, v66
	v_lshlrev_b64 v[68:69], 10, v[66:67]
	v_lshl_add_u64 v[72:73], v[68:69], 0, v[136:137]
	v_readlane_b32 s34, v255, 6
	v_lshlrev_b64 v[74:75], 2, v[72:73]
	v_readlane_b32 s35, v255, 7
	v_readlane_b32 s84, v254, 45
	v_readlane_b32 s90, v254, 51
	v_lshl_add_u64 v[76:77], s[34:35], 0, v[74:75]
	global_load_dwordx4 v[164:167], v[76:77], off
	global_load_dwordx4 v[168:171], v[76:77], off offset:64
	global_load_dwordx4 v[172:175], v[76:77], off offset:512
	global_load_dwordx4 v[176:179], v[76:77], off offset:576
	v_readlane_b32 s91, v254, 52
	v_lshl_add_u64 v[72:73], v[72:73], 1, s[6:7]
	v_readlane_b32 s85, v254, 46
	v_lshl_add_u64 v[74:75], s[90:91], 0, v[74:75]
	v_readlane_b32 s86, v254, 47
	v_readlane_b32 s87, v254, 48
	v_readlane_b32 s88, v254, 49
	v_readlane_b32 s89, v254, 50
	s_waitcnt vmcnt(3) lgkmcnt(0)
	v_mov_b64_e32 v[68:69], v[164:165]
	v_mov_b64_e32 v[70:71], v[166:167]
	v_pk_add_f32 v[62:63], v[62:63], v[70:71]
	v_pk_add_f32 v[60:61], v[60:61], v[68:69]
	v_cvt_pk_bf16_f32 v69, v62, v63
	v_cvt_pk_bf16_f32 v68, v60, v61
	global_store_dwordx4 v[74:75], v[60:63], off
	global_store_dwordx2 v[72:73], v[68:69], off
	v_mul_f32_e32 v61, v61, v61
	v_mul_f32_e32 v63, v63, v63
	v_fmac_f32_e32 v61, v60, v60
	v_fmac_f32_e32 v63, v62, v62
	v_add_f32_e32 v60, v61, v63
	s_waitcnt vmcnt(4) lgkmcnt(0)
	v_mov_b64_e32 v[68:69], v[168:169]
	v_mov_b64_e32 v[70:71], v[170:171]
	v_pk_add_f32 v[58:59], v[58:59], v[70:71]
	v_pk_add_f32 v[56:57], v[56:57], v[68:69]
	v_cvt_pk_bf16_f32 v69, v58, v59
	v_cvt_pk_bf16_f32 v68, v56, v57
	global_store_dwordx4 v[74:75], v[56:59], off offset:64
	global_store_dwordx2 v[72:73], v[68:69], off offset:32
	v_mul_f32_e32 v57, v57, v57
	v_mul_f32_e32 v59, v59, v59
	v_fmac_f32_e32 v57, v56, v56
	v_fmac_f32_e32 v59, v58, v58
	v_add_f32_e32 v56, v57, v59
	v_add_f32_e32 v56, v60, v56
	s_waitcnt vmcnt(5) lgkmcnt(0)
	v_mov_b64_e32 v[68:69], v[172:173]
	v_mov_b64_e32 v[70:71], v[174:175]
	v_pk_add_f32 v[54:55], v[54:55], v[70:71]
	v_pk_add_f32 v[52:53], v[52:53], v[68:69]
	v_cvt_pk_bf16_f32 v69, v54, v55
	v_cvt_pk_bf16_f32 v68, v52, v53
	global_store_dwordx4 v[74:75], v[52:55], off offset:512
	global_store_dwordx2 v[72:73], v[68:69], off offset:256
	v_mul_f32_e32 v53, v53, v53
	v_mul_f32_e32 v55, v55, v55
	v_fmac_f32_e32 v53, v52, v52
	v_fmac_f32_e32 v55, v54, v54
	v_add_f32_e32 v52, v53, v55
	v_add_f32_e32 v54, v56, v52
	s_waitcnt vmcnt(6) lgkmcnt(0)
	v_mov_b64_e32 v[68:69], v[176:177]
	v_mov_b64_e32 v[70:71], v[178:179]
	v_pk_add_f32 v[52:53], v[50:51], v[70:71]
	v_pk_add_f32 v[50:51], v[48:49], v[68:69]
	v_mul_f32_e32 v49, v53, v53
	v_mul_f32_e32 v48, v51, v51
	v_fmac_f32_e32 v48, v50, v50
	v_fmac_f32_e32 v49, v52, v52
	v_add_f32_e32 v48, v48, v49
	v_add_f32_e32 v48, v54, v48
	ds_bpermute_b32 v49, v118, v48
	global_store_dwordx4 v[74:75], v[50:53], off offset:576
	s_waitcnt lgkmcnt(0)
	v_add_f32_e32 v48, v48, v49
	ds_bpermute_b32 v49, v116, v48
	v_cvt_pk_bf16_f32 v50, v50, v51
	v_cvt_pk_bf16_f32 v51, v52, v53
	global_store_dwordx2 v[72:73], v[50:51], off offset:288
	s_and_saveexec_b64 s[54:55], s[0:1]
	s_cbranch_execz .LBB0_1174
	v_readlane_b32 s34, v254, 43
	v_lshlrev_b64 v[50:51], 6, v[66:67]
	v_readlane_b32 s35, v254, 44
	v_lshl_add_u64 v[50:51], s[42:43], 0, v[50:51]
	s_mov_b32 s31, s35
	v_lshl_add_u64 v[50:51], s[52:53], 2, v[50:51]
	s_lshl_b32 s34, s64, 2
	v_writelane_b32 v254, s30, 43
	v_lshl_add_u64 v[50:51], v[50:51], 0, s[34:35]
	s_waitcnt lgkmcnt(0)
	v_add_f32_e32 v48, v48, v49
	v_writelane_b32 v254, s31, 44
	global_store_dword v[50:51], v48, off
.LBB0_1174:
	s_or_b64 exec, exec, s[54:55]
	v_add_u32_e32 v48, 0x90, v138
	s_waitcnt lgkmcnt(0)
	v_ashrrev_i32_e32 v49, 31, v48
	v_lshlrev_b64 v[50:51], 10, v[48:49]
	v_lshl_add_u64 v[54:55], v[50:51], 0, v[136:137]
	v_readlane_b32 s34, v255, 6
	v_lshlrev_b64 v[56:57], 2, v[54:55]
	v_readlane_b32 s35, v255, 7
	v_readlane_b32 s84, v254, 45
	v_readlane_b32 s90, v254, 51
	v_lshl_add_u64 v[58:59], s[34:35], 0, v[56:57]
	global_load_dwordx4 v[164:167], v[58:59], off
	global_load_dwordx4 v[168:171], v[58:59], off offset:64
	global_load_dwordx4 v[172:175], v[58:59], off offset:512
	global_load_dwordx4 v[176:179], v[58:59], off offset:576
	v_readlane_b32 s91, v254, 52
	v_lshl_add_u64 v[54:55], v[54:55], 1, s[6:7]
	v_readlane_b32 s85, v254, 46
	v_lshl_add_u64 v[56:57], s[90:91], 0, v[56:57]
	v_readlane_b32 s86, v254, 47
	v_readlane_b32 s87, v254, 48
	v_readlane_b32 s88, v254, 49
	v_readlane_b32 s89, v254, 50
	s_waitcnt vmcnt(3) lgkmcnt(0)
	v_mov_b64_e32 v[50:51], v[164:165]
	v_mov_b64_e32 v[52:53], v[166:167]
	v_pk_add_f32 v[46:47], v[46:47], v[52:53]
	v_pk_add_f32 v[44:45], v[44:45], v[50:51]
	v_cvt_pk_bf16_f32 v51, v46, v47
	v_cvt_pk_bf16_f32 v50, v44, v45
	global_store_dwordx4 v[56:57], v[44:47], off
	global_store_dwordx2 v[54:55], v[50:51], off
	v_mul_f32_e32 v45, v45, v45
	v_mul_f32_e32 v47, v47, v47
	v_fmac_f32_e32 v45, v44, v44
	v_fmac_f32_e32 v47, v46, v46
	v_add_f32_e32 v44, v45, v47
	s_waitcnt vmcnt(4) lgkmcnt(0)
	v_mov_b64_e32 v[50:51], v[168:169]
	v_mov_b64_e32 v[52:53], v[170:171]
	v_pk_add_f32 v[42:43], v[42:43], v[52:53]
	v_pk_add_f32 v[40:41], v[40:41], v[50:51]
	v_cvt_pk_bf16_f32 v51, v42, v43
	v_cvt_pk_bf16_f32 v50, v40, v41
	global_store_dwordx4 v[56:57], v[40:43], off offset:64
	global_store_dwordx2 v[54:55], v[50:51], off offset:32
	v_mul_f32_e32 v41, v41, v41
	v_mul_f32_e32 v43, v43, v43
	v_fmac_f32_e32 v41, v40, v40
	v_fmac_f32_e32 v43, v42, v42
	v_add_f32_e32 v40, v41, v43
	v_add_f32_e32 v40, v44, v40
	s_waitcnt vmcnt(5) lgkmcnt(0)
	v_mov_b64_e32 v[50:51], v[172:173]
	v_mov_b64_e32 v[52:53], v[174:175]
	v_pk_add_f32 v[38:39], v[38:39], v[52:53]
	v_pk_add_f32 v[36:37], v[36:37], v[50:51]
	v_cvt_pk_bf16_f32 v51, v38, v39
	v_cvt_pk_bf16_f32 v50, v36, v37
	global_store_dwordx4 v[56:57], v[36:39], off offset:512
	global_store_dwordx2 v[54:55], v[50:51], off offset:256
	v_mul_f32_e32 v37, v37, v37
	v_mul_f32_e32 v39, v39, v39
	v_fmac_f32_e32 v37, v36, v36
	v_fmac_f32_e32 v39, v38, v38
	v_add_f32_e32 v36, v37, v39
	v_add_f32_e32 v38, v40, v36
	s_waitcnt vmcnt(6) lgkmcnt(0)
	v_mov_b64_e32 v[50:51], v[176:177]
	v_mov_b64_e32 v[52:53], v[178:179]
	v_pk_add_f32 v[36:37], v[34:35], v[52:53]
	v_pk_add_f32 v[34:35], v[32:33], v[50:51]
	v_mul_f32_e32 v33, v37, v37
	v_mul_f32_e32 v32, v35, v35
	v_fmac_f32_e32 v32, v34, v34
	v_fmac_f32_e32 v33, v36, v36
	v_add_f32_e32 v32, v32, v33
	v_add_f32_e32 v32, v38, v32
	ds_bpermute_b32 v33, v118, v32
	global_store_dwordx4 v[56:57], v[34:37], off offset:576
	s_waitcnt lgkmcnt(0)
	v_add_f32_e32 v32, v32, v33
	ds_bpermute_b32 v33, v116, v32
	v_cvt_pk_bf16_f32 v34, v34, v35
	v_cvt_pk_bf16_f32 v35, v36, v37
	global_store_dwordx2 v[54:55], v[34:35], off offset:288
	s_and_saveexec_b64 s[54:55], s[0:1]
	s_cbranch_execz .LBB0_1176
	v_readlane_b32 s34, v254, 43
	v_lshlrev_b64 v[34:35], 6, v[48:49]
	v_readlane_b32 s35, v254, 44
	v_lshl_add_u64 v[34:35], s[42:43], 0, v[34:35]
	s_mov_b32 s31, s35
	v_lshl_add_u64 v[34:35], s[52:53], 2, v[34:35]
	s_lshl_b32 s34, s64, 2
	v_writelane_b32 v254, s30, 43
	v_lshl_add_u64 v[34:35], v[34:35], 0, s[34:35]
	s_waitcnt lgkmcnt(0)
	v_add_f32_e32 v32, v32, v33
	v_writelane_b32 v254, s31, 44
	global_store_dword v[34:35], v32, off
.LBB0_1176:
	s_or_b64 exec, exec, s[54:55]
	v_add_u32_e32 v32, 0xa0, v138
	s_waitcnt lgkmcnt(0)
	v_ashrrev_i32_e32 v33, 31, v32
	v_lshlrev_b64 v[34:35], 10, v[32:33]
	v_lshl_add_u64 v[38:39], v[34:35], 0, v[136:137]
	v_readlane_b32 s34, v255, 6
	v_lshlrev_b64 v[40:41], 2, v[38:39]
	v_readlane_b32 s35, v255, 7
	v_readlane_b32 s84, v254, 45
	v_readlane_b32 s90, v254, 51
	v_lshl_add_u64 v[42:43], s[34:35], 0, v[40:41]
	global_load_dwordx4 v[164:167], v[42:43], off
	global_load_dwordx4 v[168:171], v[42:43], off offset:64
	global_load_dwordx4 v[172:175], v[42:43], off offset:512
	global_load_dwordx4 v[176:179], v[42:43], off offset:576
	v_readlane_b32 s91, v254, 52
	v_lshl_add_u64 v[38:39], v[38:39], 1, s[6:7]
	v_readlane_b32 s85, v254, 46
	v_lshl_add_u64 v[40:41], s[90:91], 0, v[40:41]
	v_readlane_b32 s86, v254, 47
	v_readlane_b32 s87, v254, 48
	v_readlane_b32 s88, v254, 49
	v_readlane_b32 s89, v254, 50
	s_waitcnt vmcnt(3) lgkmcnt(0)
	v_mov_b64_e32 v[34:35], v[164:165]
	v_mov_b64_e32 v[36:37], v[166:167]
	v_pk_add_f32 v[30:31], v[30:31], v[36:37]
	v_pk_add_f32 v[28:29], v[28:29], v[34:35]
	v_cvt_pk_bf16_f32 v35, v30, v31
	v_cvt_pk_bf16_f32 v34, v28, v29
	global_store_dwordx4 v[40:41], v[28:31], off
	global_store_dwordx2 v[38:39], v[34:35], off
	v_mul_f32_e32 v29, v29, v29
	v_mul_f32_e32 v31, v31, v31
	v_fmac_f32_e32 v29, v28, v28
	v_fmac_f32_e32 v31, v30, v30
	v_add_f32_e32 v28, v29, v31
	s_waitcnt vmcnt(4) lgkmcnt(0)
	v_mov_b64_e32 v[34:35], v[168:169]
	v_mov_b64_e32 v[36:37], v[170:171]
	v_pk_add_f32 v[26:27], v[26:27], v[36:37]
	v_pk_add_f32 v[24:25], v[24:25], v[34:35]
	v_cvt_pk_bf16_f32 v35, v26, v27
	v_cvt_pk_bf16_f32 v34, v24, v25
	global_store_dwordx4 v[40:41], v[24:27], off offset:64
	global_store_dwordx2 v[38:39], v[34:35], off offset:32
	v_mul_f32_e32 v25, v25, v25
	v_mul_f32_e32 v27, v27, v27
	v_fmac_f32_e32 v25, v24, v24
	v_fmac_f32_e32 v27, v26, v26
	v_add_f32_e32 v24, v25, v27
	v_add_f32_e32 v24, v28, v24
	s_waitcnt vmcnt(5) lgkmcnt(0)
	v_mov_b64_e32 v[34:35], v[172:173]
	v_mov_b64_e32 v[36:37], v[174:175]
	v_pk_add_f32 v[22:23], v[22:23], v[36:37]
	v_pk_add_f32 v[20:21], v[20:21], v[34:35]
	v_cvt_pk_bf16_f32 v35, v22, v23
	v_cvt_pk_bf16_f32 v34, v20, v21
	global_store_dwordx4 v[40:41], v[20:23], off offset:512
	global_store_dwordx2 v[38:39], v[34:35], off offset:256
	v_mul_f32_e32 v21, v21, v21
	v_mul_f32_e32 v23, v23, v23
	v_fmac_f32_e32 v21, v20, v20
	v_fmac_f32_e32 v23, v22, v22
	v_add_f32_e32 v20, v21, v23
	v_add_f32_e32 v22, v24, v20
	s_waitcnt vmcnt(6) lgkmcnt(0)
	v_mov_b64_e32 v[34:35], v[176:177]
	v_mov_b64_e32 v[36:37], v[178:179]
	v_pk_add_f32 v[20:21], v[18:19], v[36:37]
	v_pk_add_f32 v[18:19], v[16:17], v[34:35]
	v_mul_f32_e32 v17, v21, v21
	v_mul_f32_e32 v16, v19, v19
	v_fmac_f32_e32 v16, v18, v18
	v_fmac_f32_e32 v17, v20, v20
	v_add_f32_e32 v16, v16, v17
	v_add_f32_e32 v16, v22, v16
	ds_bpermute_b32 v17, v118, v16
	global_store_dwordx4 v[40:41], v[18:21], off offset:576
	s_waitcnt lgkmcnt(0)
	v_add_f32_e32 v16, v16, v17
	ds_bpermute_b32 v17, v116, v16
	v_cvt_pk_bf16_f32 v18, v18, v19
	v_cvt_pk_bf16_f32 v19, v20, v21
	global_store_dwordx2 v[38:39], v[18:19], off offset:288
	s_and_saveexec_b64 s[54:55], s[0:1]
	s_cbranch_execz .LBB0_1178
	v_readlane_b32 s34, v254, 43
	v_lshlrev_b64 v[18:19], 6, v[32:33]
	v_readlane_b32 s35, v254, 44
	v_lshl_add_u64 v[18:19], s[42:43], 0, v[18:19]
	s_mov_b32 s31, s35
	v_lshl_add_u64 v[18:19], s[52:53], 2, v[18:19]
	s_lshl_b32 s34, s64, 2
	v_writelane_b32 v254, s30, 43
	v_lshl_add_u64 v[18:19], v[18:19], 0, s[34:35]
	s_waitcnt lgkmcnt(0)
	v_add_f32_e32 v16, v16, v17
	v_writelane_b32 v254, s31, 44
	global_store_dword v[18:19], v16, off
.LBB0_1178:
	s_or_b64 exec, exec, s[54:55]
	v_add_u32_e32 v16, 0xb0, v138
	s_waitcnt lgkmcnt(0)
	v_ashrrev_i32_e32 v17, 31, v16
	v_lshlrev_b64 v[18:19], 10, v[16:17]
	v_lshl_add_u64 v[22:23], v[18:19], 0, v[136:137]
	v_readlane_b32 s34, v255, 6
	v_lshlrev_b64 v[24:25], 2, v[22:23]
	v_readlane_b32 s35, v255, 7
	v_readlane_b32 s84, v254, 45
	v_readlane_b32 s90, v254, 51
	v_lshl_add_u64 v[26:27], s[34:35], 0, v[24:25]
	global_load_dwordx4 v[164:167], v[26:27], off
	global_load_dwordx4 v[168:171], v[26:27], off offset:64
	global_load_dwordx4 v[172:175], v[26:27], off offset:512
	global_load_dwordx4 v[176:179], v[26:27], off offset:576
	v_readlane_b32 s91, v254, 52
	v_lshl_add_u64 v[22:23], v[22:23], 1, s[6:7]
	v_readlane_b32 s85, v254, 46
	v_lshl_add_u64 v[24:25], s[90:91], 0, v[24:25]
	v_readlane_b32 s86, v254, 47
	v_readlane_b32 s87, v254, 48
	v_readlane_b32 s88, v254, 49
	v_readlane_b32 s89, v254, 50
	s_waitcnt vmcnt(3) lgkmcnt(0)
	v_mov_b64_e32 v[18:19], v[164:165]
	v_mov_b64_e32 v[20:21], v[166:167]
	v_pk_add_f32 v[14:15], v[14:15], v[20:21]
	v_pk_add_f32 v[12:13], v[12:13], v[18:19]
	v_cvt_pk_bf16_f32 v19, v14, v15
	v_cvt_pk_bf16_f32 v18, v12, v13
	global_store_dwordx4 v[24:25], v[12:15], off
	global_store_dwordx2 v[22:23], v[18:19], off
	v_mul_f32_e32 v13, v13, v13
	v_mul_f32_e32 v15, v15, v15
	v_fmac_f32_e32 v13, v12, v12
	v_fmac_f32_e32 v15, v14, v14
	v_add_f32_e32 v12, v13, v15
	s_waitcnt vmcnt(4) lgkmcnt(0)
	v_mov_b64_e32 v[18:19], v[168:169]
	v_mov_b64_e32 v[20:21], v[170:171]
	v_pk_add_f32 v[10:11], v[10:11], v[20:21]
	v_pk_add_f32 v[8:9], v[8:9], v[18:19]
	v_cvt_pk_bf16_f32 v19, v10, v11
	v_cvt_pk_bf16_f32 v18, v8, v9
	global_store_dwordx4 v[24:25], v[8:11], off offset:64
	global_store_dwordx2 v[22:23], v[18:19], off offset:32
	v_mul_f32_e32 v9, v9, v9
	v_mul_f32_e32 v11, v11, v11
	v_fmac_f32_e32 v9, v8, v8
	v_fmac_f32_e32 v11, v10, v10
	v_add_f32_e32 v8, v9, v11
	v_add_f32_e32 v8, v12, v8
	s_waitcnt vmcnt(5) lgkmcnt(0)
	v_mov_b64_e32 v[18:19], v[172:173]
	v_mov_b64_e32 v[20:21], v[174:175]
	v_pk_add_f32 v[6:7], v[6:7], v[20:21]
	v_pk_add_f32 v[4:5], v[4:5], v[18:19]
	v_cvt_pk_bf16_f32 v19, v6, v7
	v_cvt_pk_bf16_f32 v18, v4, v5
	global_store_dwordx4 v[24:25], v[4:7], off offset:512
	global_store_dwordx2 v[22:23], v[18:19], off offset:256
	v_mul_f32_e32 v5, v5, v5
	v_mul_f32_e32 v7, v7, v7
	v_fmac_f32_e32 v5, v4, v4
	v_fmac_f32_e32 v7, v6, v6
	v_add_f32_e32 v4, v5, v7
	v_add_f32_e32 v6, v8, v4
	s_waitcnt vmcnt(6) lgkmcnt(0)
	v_mov_b64_e32 v[18:19], v[176:177]
	v_mov_b64_e32 v[20:21], v[178:179]
	v_pk_add_f32 v[4:5], v[2:3], v[20:21]
	v_pk_add_f32 v[2:3], v[0:1], v[18:19]
	v_mul_f32_e32 v1, v5, v5
	v_mul_f32_e32 v0, v3, v3
	v_fmac_f32_e32 v0, v2, v2
	v_fmac_f32_e32 v1, v4, v4
	v_add_f32_e32 v0, v0, v1
	v_add_f32_e32 v0, v6, v0
	ds_bpermute_b32 v1, v118, v0
	global_store_dwordx4 v[24:25], v[2:5], off offset:576
	s_waitcnt lgkmcnt(0)
	v_add_f32_e32 v0, v0, v1
	ds_bpermute_b32 v1, v116, v0
	v_cvt_pk_bf16_f32 v2, v2, v3
	v_cvt_pk_bf16_f32 v3, v4, v5
	global_store_dwordx2 v[22:23], v[2:3], off offset:288
	s_and_saveexec_b64 s[54:55], s[0:1]
	s_cbranch_execz .LBB0_1180
	v_readlane_b32 s34, v254, 43
	v_lshlrev_b64 v[2:3], 6, v[16:17]
	v_readlane_b32 s35, v254, 44
	v_lshl_add_u64 v[2:3], s[42:43], 0, v[2:3]
	s_mov_b32 s31, s35
	v_lshl_add_u64 v[2:3], s[52:53], 2, v[2:3]
	s_lshl_b32 s34, s64, 2
	v_writelane_b32 v254, s30, 43
	v_lshl_add_u64 v[2:3], v[2:3], 0, s[34:35]
	s_waitcnt lgkmcnt(0)
	v_add_f32_e32 v0, v0, v1
	v_writelane_b32 v254, s31, 44
	global_store_dword v[2:3], v0, off

.LBB0_1685:
	v_lshl_add_u32 v138, s27, 8, v144
	v_lshl_or_b32 v136, s26, 8, v146
	v_ashrrev_i32_e32 v139, 31, v138
	v_ashrrev_i32_e32 v137, 31, v136
	v_lshlrev_b64 v[140:141], 10, v[138:139]
	v_readlane_b32 s84, v254, 45
	v_lshl_add_u64 v[142:143], v[140:141], 0, v[136:137]
	v_readlane_b32 s90, v254, 51
	v_readlane_b32 s91, v254, 52
	s_lshl_b32 s50, s26, 2
	v_cndmask_b32_e64 v152, 0, 1, s[44:45]
	v_lshl_add_u64 v[140:141], v[142:143], 2, s[90:91]
	global_load_dwordx4 v[164:167], v[140:141], off
	global_load_dwordx4 v[168:171], v[140:141], off offset:64
	global_load_dwordx4 v[172:175], v[140:141], off offset:512
	global_load_dwordx4 v[176:179], v[140:141], off offset:576
	s_ashr_i32 s51, s50, 31
	v_cmp_ne_u32_e64 s[38:39], 1, v152
	s_andn2_b64 vcc, exec, s[44:45]
	v_readlane_b32 s33, v255, 5
	v_readlane_b32 s85, v254, 46
	v_readlane_b32 s86, v254, 47
	v_readlane_b32 s87, v254, 48
	v_readlane_b32 s88, v254, 49
	v_readlane_b32 s89, v254, 50
	s_waitcnt vmcnt(3)
	v_mov_b64_e32 v[148:149], v[164:165]
	v_mov_b64_e32 v[150:151], v[166:167]
	v_pk_add_f32 v[128:129], v[128:129], v[150:151]
	v_pk_add_f32 v[126:127], v[126:127], v[148:149]
	global_store_dwordx4 v[140:141], v[126:129], off
	s_cbranch_vccnz .LBB0_1728
	v_cvt_pk_bf16_f32 v148, v126, v127
	v_mul_f32_e32 v127, v127, v127
	v_cvt_pk_bf16_f32 v149, v128, v129
	v_lshl_add_u64 v[142:143], v[142:143], 1, s[4:5]
	v_fmac_f32_e32 v127, v126, v126
	v_mul_f32_e32 v126, v129, v129
	global_store_dwordx2 v[142:143], v[148:149], off
	v_fmac_f32_e32 v126, v128, v128
	v_add_f32_e32 v150, v127, v126
	s_waitcnt vmcnt(4)
	v_mov_b64_e32 v[126:127], v[168:169]
	v_mov_b64_e32 v[128:129], v[170:171]
	v_pk_add_f32 v[128:129], v[124:125], v[128:129]
	v_pk_add_f32 v[126:127], v[122:123], v[126:127]
	global_store_dwordx4 v[140:141], v[126:129], off offset:64
	v_cvt_pk_bf16_f32 v148, v126, v127
	v_cvt_pk_bf16_f32 v149, v128, v129
	v_mul_f32_e32 v127, v127, v127
	v_fmac_f32_e32 v127, v126, v126
	v_mul_f32_e32 v126, v129, v129
	v_fmac_f32_e32 v126, v128, v128
	global_store_dwordx2 v[142:143], v[148:149], off offset:32
	v_add_f32_e32 v126, v127, v126
	v_add_f32_e32 v150, v150, v126
	s_waitcnt vmcnt(5)
	v_mov_b64_e32 v[126:127], v[172:173]
	v_mov_b64_e32 v[128:129], v[174:175]
	v_pk_add_f32 v[128:129], v[120:121], v[128:129]
	v_pk_add_f32 v[126:127], v[118:119], v[126:127]
	global_store_dwordx4 v[140:141], v[126:129], off offset:512
	v_cvt_pk_bf16_f32 v148, v126, v127
	v_cvt_pk_bf16_f32 v149, v128, v129
	v_mul_f32_e32 v127, v127, v127
	v_fmac_f32_e32 v127, v126, v126
	v_mul_f32_e32 v126, v129, v129
	v_fmac_f32_e32 v126, v128, v128
	global_store_dwordx2 v[142:143], v[148:149], off offset:256
	v_add_f32_e32 v126, v127, v126
	v_add_f32_e32 v150, v150, v126
	s_waitcnt vmcnt(6)
	v_mov_b64_e32 v[126:127], v[176:177]
	v_mov_b64_e32 v[128:129], v[178:179]
	v_pk_add_f32 v[128:129], v[116:117], v[128:129]
	v_pk_add_f32 v[126:127], v[114:115], v[126:127]
	global_store_dwordx4 v[140:141], v[126:129], off offset:576
	v_cvt_pk_bf16_f32 v148, v126, v127
	v_cvt_pk_bf16_f32 v149, v128, v129
	v_mul_f32_e32 v127, v127, v127
	v_fmac_f32_e32 v127, v126, v126
	v_mul_f32_e32 v126, v129, v129
	v_fmac_f32_e32 v126, v128, v128
	v_and_b32_e32 v128, 64, v197
	v_add_f32_e32 v126, v127, v126
	v_xor_b32_e32 v127, 16, v197
	v_add_u32_e32 v128, 64, v128
	v_cmp_lt_i32_e32 vcc, v127, v128
	v_add_f32_e32 v126, v150, v126
	global_store_dwordx2 v[142:143], v[148:149], off offset:288
	v_cndmask_b32_e32 v127, v197, v127, vcc
	v_lshlrev_b32_e32 v127, 2, v127
	ds_bpermute_b32 v127, v127, v126
	s_waitcnt lgkmcnt(0)
	v_add_f32_e32 v126, v126, v127
	v_xor_b32_e32 v127, 32, v197
	v_cmp_lt_i32_e32 vcc, v127, v128
	s_nop 1
	v_cndmask_b32_e32 v127, v197, v127, vcc
	v_lshlrev_b32_e32 v127, 2, v127
	ds_bpermute_b32 v127, v127, v126
	s_and_saveexec_b64 s[52:53], s[0:1]
	s_cbranch_execz .LBB0_1688
	v_lshlrev_b64 v[128:129], 6, v[138:139]
	v_readlane_b32 s26, v254, 43
	v_lshl_add_u64 v[128:129], s[30:31], 0, v[128:129]
	v_readlane_b32 s27, v254, 44
	v_lshl_add_u64 v[128:129], s[50:51], 2, v[128:129]
	s_mov_b32 s29, s27
	s_lshl_b32 s28, s65, 2
	v_writelane_b32 v254, s26, 43
	v_lshl_add_u64 v[128:129], v[128:129], 0, s[28:29]
	s_waitcnt lgkmcnt(0)
	v_add_f32_e32 v126, v126, v127
	v_writelane_b32 v254, s27, 44
	global_store_dword v[128:129], v126, off

.LBB0_1690:
	s_nop 1
	v_or_b32_e32 v116, 16, v138
	v_ashrrev_i32_e32 v117, 31, v116
	v_lshlrev_b64 v[114:115], 10, v[116:117]
	v_readlane_b32 s84, v254, 45
	v_lshl_add_u64 v[118:119], v[114:115], 0, v[136:137]
	v_readlane_b32 s90, v254, 51
	v_readlane_b32 s91, v254, 52
	s_and_b64 vcc, exec, s[38:39]
	v_readlane_b32 s85, v254, 46
	v_lshl_add_u64 v[114:115], v[118:119], 2, s[90:91]
	global_load_dwordx4 v[164:167], v[114:115], off
	global_load_dwordx4 v[168:171], v[114:115], off offset:64
	global_load_dwordx4 v[172:175], v[114:115], off offset:512
	global_load_dwordx4 v[176:179], v[114:115], off offset:576
	v_readlane_b32 s86, v254, 47
	v_readlane_b32 s87, v254, 48
	v_readlane_b32 s88, v254, 49
	v_readlane_b32 s89, v254, 50
	s_waitcnt vmcnt(3)
	v_mov_b64_e32 v[120:121], v[164:165]
	v_mov_b64_e32 v[122:123], v[166:167]
	v_pk_add_f32 v[112:113], v[112:113], v[122:123]
	v_pk_add_f32 v[110:111], v[110:111], v[120:121]
	global_store_dwordx4 v[114:115], v[110:113], off
	s_cbranch_vccnz .LBB0_1729
	v_cvt_pk_bf16_f32 v120, v110, v111
	v_mul_f32_e32 v111, v111, v111
	v_cvt_pk_bf16_f32 v121, v112, v113
	v_lshl_add_u64 v[118:119], v[118:119], 1, s[4:5]
	v_fmac_f32_e32 v111, v110, v110
	v_mul_f32_e32 v110, v113, v113
	global_store_dwordx2 v[118:119], v[120:121], off
	v_fmac_f32_e32 v110, v112, v112
	v_add_f32_e32 v122, v111, v110
	s_waitcnt vmcnt(4)
	v_mov_b64_e32 v[110:111], v[168:169]
	v_mov_b64_e32 v[112:113], v[170:171]
	v_pk_add_f32 v[112:113], v[108:109], v[112:113]
	v_pk_add_f32 v[110:111], v[106:107], v[110:111]
	global_store_dwordx4 v[114:115], v[110:113], off offset:64
	v_cvt_pk_bf16_f32 v120, v110, v111
	v_cvt_pk_bf16_f32 v121, v112, v113
	v_mul_f32_e32 v111, v111, v111
	v_fmac_f32_e32 v111, v110, v110
	v_mul_f32_e32 v110, v113, v113
	v_fmac_f32_e32 v110, v112, v112
	global_store_dwordx2 v[118:119], v[120:121], off offset:32
	v_add_f32_e32 v110, v111, v110
	v_add_f32_e32 v122, v122, v110
	s_waitcnt vmcnt(5)
	v_mov_b64_e32 v[110:111], v[172:173]
	v_mov_b64_e32 v[112:113], v[174:175]
	v_pk_add_f32 v[112:113], v[104:105], v[112:113]
	v_pk_add_f32 v[110:111], v[102:103], v[110:111]
	global_store_dwordx4 v[114:115], v[110:113], off offset:512
	v_cvt_pk_bf16_f32 v120, v110, v111
	v_cvt_pk_bf16_f32 v121, v112, v113
	v_mul_f32_e32 v111, v111, v111
	v_fmac_f32_e32 v111, v110, v110
	v_mul_f32_e32 v110, v113, v113
	v_fmac_f32_e32 v110, v112, v112
	global_store_dwordx2 v[118:119], v[120:121], off offset:256
	v_add_f32_e32 v110, v111, v110
	v_add_f32_e32 v122, v122, v110
	s_waitcnt vmcnt(6)
	v_mov_b64_e32 v[110:111], v[176:177]
	v_mov_b64_e32 v[112:113], v[178:179]
	v_pk_add_f32 v[112:113], v[100:101], v[112:113]
	v_pk_add_f32 v[110:111], v[98:99], v[110:111]
	global_store_dwordx4 v[114:115], v[110:113], off offset:576
	v_cvt_pk_bf16_f32 v120, v110, v111
	v_cvt_pk_bf16_f32 v121, v112, v113
	v_mul_f32_e32 v111, v111, v111
	v_fmac_f32_e32 v111, v110, v110
	v_mul_f32_e32 v110, v113, v113
	v_fmac_f32_e32 v110, v112, v112
	v_and_b32_e32 v112, 64, v197
	v_add_f32_e32 v110, v111, v110
	v_xor_b32_e32 v111, 16, v197
	v_add_u32_e32 v112, 64, v112
	v_cmp_lt_i32_e32 vcc, v111, v112
	v_add_f32_e32 v110, v122, v110
	global_store_dwordx2 v[118:119], v[120:121], off offset:288
	v_cndmask_b32_e32 v111, v197, v111, vcc
	v_lshlrev_b32_e32 v111, 2, v111
	ds_bpermute_b32 v111, v111, v110
	s_waitcnt lgkmcnt(0)
	v_add_f32_e32 v110, v110, v111
	v_xor_b32_e32 v111, 32, v197
	v_cmp_lt_i32_e32 vcc, v111, v112
	s_nop 1
	v_cndmask_b32_e32 v111, v197, v111, vcc
	v_lshlrev_b32_e32 v111, 2, v111
	ds_bpermute_b32 v111, v111, v110
	s_and_saveexec_b64 s[52:53], s[0:1]
	s_cbranch_execz .LBB0_1693
	v_lshlrev_b64 v[112:113], 6, v[116:117]
	v_readlane_b32 s26, v254, 43
	v_lshl_add_u64 v[112:113], s[30:31], 0, v[112:113]
	v_readlane_b32 s27, v254, 44
	v_lshl_add_u64 v[112:113], s[50:51], 2, v[112:113]
	s_mov_b32 s29, s27
	s_lshl_b32 s28, s65, 2
	v_writelane_b32 v254, s26, 43
	v_lshl_add_u64 v[112:113], v[112:113], 0, s[28:29]
	s_waitcnt lgkmcnt(0)
	v_add_f32_e32 v110, v110, v111
	v_writelane_b32 v254, s27, 44
	global_store_dword v[112:113], v110, off

.LBB0_1695:
	s_nop 1
	v_or_b32_e32 v100, 32, v138
	v_ashrrev_i32_e32 v101, 31, v100
	v_lshlrev_b64 v[98:99], 10, v[100:101]
	v_readlane_b32 s84, v254, 45
	v_lshl_add_u64 v[102:103], v[98:99], 0, v[136:137]
	v_readlane_b32 s90, v254, 51
	v_readlane_b32 s91, v254, 52
	s_and_b64 vcc, exec, s[38:39]
	v_readlane_b32 s85, v254, 46
	v_lshl_add_u64 v[98:99], v[102:103], 2, s[90:91]
	global_load_dwordx4 v[164:167], v[98:99], off
	global_load_dwordx4 v[168:171], v[98:99], off offset:64
	global_load_dwordx4 v[172:175], v[98:99], off offset:512
	global_load_dwordx4 v[176:179], v[98:99], off offset:576
	v_readlane_b32 s86, v254, 47
	v_readlane_b32 s87, v254, 48
	v_readlane_b32 s88, v254, 49
	v_readlane_b32 s89, v254, 50
	s_waitcnt vmcnt(3)
	v_mov_b64_e32 v[104:105], v[164:165]
	v_mov_b64_e32 v[106:107], v[166:167]
	v_pk_add_f32 v[96:97], v[96:97], v[106:107]
	v_pk_add_f32 v[94:95], v[94:95], v[104:105]
	global_store_dwordx4 v[98:99], v[94:97], off
	s_cbranch_vccnz .LBB0_1730
	v_cvt_pk_bf16_f32 v104, v94, v95
	v_mul_f32_e32 v95, v95, v95
	v_cvt_pk_bf16_f32 v105, v96, v97
	v_lshl_add_u64 v[102:103], v[102:103], 1, s[4:5]
	v_fmac_f32_e32 v95, v94, v94
	v_mul_f32_e32 v94, v97, v97
	global_store_dwordx2 v[102:103], v[104:105], off
	v_fmac_f32_e32 v94, v96, v96
	v_add_f32_e32 v106, v95, v94
	s_waitcnt vmcnt(4)
	v_mov_b64_e32 v[94:95], v[168:169]
	v_mov_b64_e32 v[96:97], v[170:171]
	v_pk_add_f32 v[96:97], v[92:93], v[96:97]
	v_pk_add_f32 v[94:95], v[90:91], v[94:95]
	global_store_dwordx4 v[98:99], v[94:97], off offset:64
	v_cvt_pk_bf16_f32 v104, v94, v95
	v_cvt_pk_bf16_f32 v105, v96, v97
	v_mul_f32_e32 v95, v95, v95
	v_fmac_f32_e32 v95, v94, v94
	v_mul_f32_e32 v94, v97, v97
	v_fmac_f32_e32 v94, v96, v96
	global_store_dwordx2 v[102:103], v[104:105], off offset:32
	v_add_f32_e32 v94, v95, v94
	v_add_f32_e32 v106, v106, v94
	s_waitcnt vmcnt(5)
	v_mov_b64_e32 v[94:95], v[172:173]
	v_mov_b64_e32 v[96:97], v[174:175]
	v_pk_add_f32 v[96:97], v[88:89], v[96:97]
	v_pk_add_f32 v[94:95], v[86:87], v[94:95]
	global_store_dwordx4 v[98:99], v[94:97], off offset:512
	v_cvt_pk_bf16_f32 v104, v94, v95
	v_cvt_pk_bf16_f32 v105, v96, v97
	v_mul_f32_e32 v95, v95, v95
	v_fmac_f32_e32 v95, v94, v94
	v_mul_f32_e32 v94, v97, v97
	v_fmac_f32_e32 v94, v96, v96
	global_store_dwordx2 v[102:103], v[104:105], off offset:256
	v_add_f32_e32 v94, v95, v94
	v_add_f32_e32 v106, v106, v94
	s_waitcnt vmcnt(6)
	v_mov_b64_e32 v[94:95], v[176:177]
	v_mov_b64_e32 v[96:97], v[178:179]
	v_pk_add_f32 v[96:97], v[84:85], v[96:97]
	v_pk_add_f32 v[94:95], v[82:83], v[94:95]
	global_store_dwordx4 v[98:99], v[94:97], off offset:576
	v_cvt_pk_bf16_f32 v104, v94, v95
	v_cvt_pk_bf16_f32 v105, v96, v97
	v_mul_f32_e32 v95, v95, v95
	v_fmac_f32_e32 v95, v94, v94
	v_mul_f32_e32 v94, v97, v97
	v_fmac_f32_e32 v94, v96, v96
	v_and_b32_e32 v96, 64, v197
	v_add_f32_e32 v94, v95, v94
	v_xor_b32_e32 v95, 16, v197
	v_add_u32_e32 v96, 64, v96
	v_cmp_lt_i32_e32 vcc, v95, v96
	v_add_f32_e32 v94, v106, v94
	global_store_dwordx2 v[102:103], v[104:105], off offset:288
	v_cndmask_b32_e32 v95, v197, v95, vcc
	v_lshlrev_b32_e32 v95, 2, v95
	ds_bpermute_b32 v95, v95, v94
	s_waitcnt lgkmcnt(0)
	v_add_f32_e32 v94, v94, v95
	v_xor_b32_e32 v95, 32, v197
	v_cmp_lt_i32_e32 vcc, v95, v96
	s_nop 1
	v_cndmask_b32_e32 v95, v197, v95, vcc
	v_lshlrev_b32_e32 v95, 2, v95
	ds_bpermute_b32 v95, v95, v94
	s_and_saveexec_b64 s[52:53], s[0:1]
	s_cbranch_execz .LBB0_1698
	v_lshlrev_b64 v[96:97], 6, v[100:101]
	v_readlane_b32 s26, v254, 43
	v_lshl_add_u64 v[96:97], s[30:31], 0, v[96:97]
	v_readlane_b32 s27, v254, 44
	v_lshl_add_u64 v[96:97], s[50:51], 2, v[96:97]
	s_mov_b32 s29, s27
	s_lshl_b32 s28, s65, 2
	v_writelane_b32 v254, s26, 43
	v_lshl_add_u64 v[96:97], v[96:97], 0, s[28:29]
	s_waitcnt lgkmcnt(0)
	v_add_f32_e32 v94, v94, v95
	v_writelane_b32 v254, s27, 44
	global_store_dword v[96:97], v94, off

.LBB0_1700:
	s_nop 1
	v_or_b32_e32 v84, 48, v138
	v_ashrrev_i32_e32 v85, 31, v84
	v_lshlrev_b64 v[82:83], 10, v[84:85]
	v_readlane_b32 s84, v254, 45
	v_lshl_add_u64 v[86:87], v[82:83], 0, v[136:137]
	v_readlane_b32 s90, v254, 51
	v_readlane_b32 s91, v254, 52
	s_and_b64 vcc, exec, s[38:39]
	v_readlane_b32 s85, v254, 46
	v_lshl_add_u64 v[82:83], v[86:87], 2, s[90:91]
	global_load_dwordx4 v[164:167], v[82:83], off
	global_load_dwordx4 v[168:171], v[82:83], off offset:64
	global_load_dwordx4 v[172:175], v[82:83], off offset:512
	global_load_dwordx4 v[176:179], v[82:83], off offset:576
	v_readlane_b32 s86, v254, 47
	v_readlane_b32 s87, v254, 48
	v_readlane_b32 s88, v254, 49
	v_readlane_b32 s89, v254, 50
	s_waitcnt vmcnt(3)
	v_mov_b64_e32 v[88:89], v[164:165]
	v_mov_b64_e32 v[90:91], v[166:167]
	v_pk_add_f32 v[80:81], v[80:81], v[90:91]
	v_pk_add_f32 v[78:79], v[78:79], v[88:89]
	global_store_dwordx4 v[82:83], v[78:81], off
	s_cbranch_vccnz .LBB0_1731
	v_cvt_pk_bf16_f32 v88, v78, v79
	v_mul_f32_e32 v79, v79, v79
	v_cvt_pk_bf16_f32 v89, v80, v81
	v_lshl_add_u64 v[86:87], v[86:87], 1, s[4:5]
	v_fmac_f32_e32 v79, v78, v78
	v_mul_f32_e32 v78, v81, v81
	global_store_dwordx2 v[86:87], v[88:89], off
	v_fmac_f32_e32 v78, v80, v80
	v_add_f32_e32 v90, v79, v78
	s_waitcnt vmcnt(4)
	v_mov_b64_e32 v[78:79], v[168:169]
	v_mov_b64_e32 v[80:81], v[170:171]
	v_pk_add_f32 v[80:81], v[76:77], v[80:81]
	v_pk_add_f32 v[78:79], v[74:75], v[78:79]
	global_store_dwordx4 v[82:83], v[78:81], off offset:64
	v_cvt_pk_bf16_f32 v88, v78, v79
	v_cvt_pk_bf16_f32 v89, v80, v81
	v_mul_f32_e32 v79, v79, v79
	v_fmac_f32_e32 v79, v78, v78
	v_mul_f32_e32 v78, v81, v81
	v_fmac_f32_e32 v78, v80, v80
	global_store_dwordx2 v[86:87], v[88:89], off offset:32
	v_add_f32_e32 v78, v79, v78
	v_add_f32_e32 v90, v90, v78
	s_waitcnt vmcnt(5)
	v_mov_b64_e32 v[78:79], v[172:173]
	v_mov_b64_e32 v[80:81], v[174:175]
	v_pk_add_f32 v[80:81], v[72:73], v[80:81]
	v_pk_add_f32 v[78:79], v[70:71], v[78:79]
	global_store_dwordx4 v[82:83], v[78:81], off offset:512
	v_cvt_pk_bf16_f32 v88, v78, v79
	v_cvt_pk_bf16_f32 v89, v80, v81
	v_mul_f32_e32 v79, v79, v79
	v_fmac_f32_e32 v79, v78, v78
	v_mul_f32_e32 v78, v81, v81
	v_fmac_f32_e32 v78, v80, v80
	global_store_dwordx2 v[86:87], v[88:89], off offset:256
	v_add_f32_e32 v78, v79, v78
	v_add_f32_e32 v90, v90, v78
	s_waitcnt vmcnt(6)
	v_mov_b64_e32 v[78:79], v[176:177]
	v_mov_b64_e32 v[80:81], v[178:179]
	v_pk_add_f32 v[80:81], v[68:69], v[80:81]
	v_pk_add_f32 v[78:79], v[66:67], v[78:79]
	global_store_dwordx4 v[82:83], v[78:81], off offset:576
	v_cvt_pk_bf16_f32 v88, v78, v79
	v_cvt_pk_bf16_f32 v89, v80, v81
	v_mul_f32_e32 v79, v79, v79
	v_fmac_f32_e32 v79, v78, v78
	v_mul_f32_e32 v78, v81, v81
	v_fmac_f32_e32 v78, v80, v80
	v_and_b32_e32 v80, 64, v197
	v_add_f32_e32 v78, v79, v78
	v_xor_b32_e32 v79, 16, v197
	v_add_u32_e32 v80, 64, v80
	v_cmp_lt_i32_e32 vcc, v79, v80
	v_add_f32_e32 v78, v90, v78
	global_store_dwordx2 v[86:87], v[88:89], off offset:288
	v_cndmask_b32_e32 v79, v197, v79, vcc
	v_lshlrev_b32_e32 v79, 2, v79
	ds_bpermute_b32 v79, v79, v78
	s_waitcnt lgkmcnt(0)
	v_add_f32_e32 v78, v78, v79
	v_xor_b32_e32 v79, 32, v197
	v_cmp_lt_i32_e32 vcc, v79, v80
	s_nop 1
	v_cndmask_b32_e32 v79, v197, v79, vcc
	v_lshlrev_b32_e32 v79, 2, v79
	ds_bpermute_b32 v79, v79, v78
	s_and_saveexec_b64 s[52:53], s[0:1]
	s_cbranch_execz .LBB0_1703
	v_lshlrev_b64 v[80:81], 6, v[84:85]
	v_readlane_b32 s26, v254, 43
	v_lshl_add_u64 v[80:81], s[30:31], 0, v[80:81]
	v_readlane_b32 s27, v254, 44
	v_lshl_add_u64 v[80:81], s[50:51], 2, v[80:81]
	s_mov_b32 s29, s27
	s_lshl_b32 s28, s65, 2
	v_writelane_b32 v254, s26, 43
	v_lshl_add_u64 v[80:81], v[80:81], 0, s[28:29]
	s_waitcnt lgkmcnt(0)
	v_add_f32_e32 v78, v78, v79
	v_writelane_b32 v254, s27, 44
	global_store_dword v[80:81], v78, off

.LBB0_1705:
	s_nop 1
	v_add_u32_e32 v68, 0x80, v138
	v_ashrrev_i32_e32 v69, 31, v68
	v_lshlrev_b64 v[66:67], 10, v[68:69]
	v_readlane_b32 s84, v254, 45
	v_lshl_add_u64 v[70:71], v[66:67], 0, v[136:137]
	v_readlane_b32 s90, v254, 51
	v_readlane_b32 s91, v254, 52
	s_and_b64 vcc, exec, s[38:39]
	v_readlane_b32 s85, v254, 46
	v_lshl_add_u64 v[66:67], v[70:71], 2, s[90:91]
	global_load_dwordx4 v[164:167], v[66:67], off
	global_load_dwordx4 v[168:171], v[66:67], off offset:64
	global_load_dwordx4 v[172:175], v[66:67], off offset:512
	global_load_dwordx4 v[176:179], v[66:67], off offset:576
	v_readlane_b32 s86, v254, 47
	v_readlane_b32 s87, v254, 48
	v_readlane_b32 s88, v254, 49
	v_readlane_b32 s89, v254, 50
	s_waitcnt vmcnt(3)
	v_mov_b64_e32 v[72:73], v[164:165]
	v_mov_b64_e32 v[74:75], v[166:167]
	v_pk_add_f32 v[62:63], v[62:63], v[74:75]
	v_pk_add_f32 v[60:61], v[60:61], v[72:73]
	global_store_dwordx4 v[66:67], v[60:63], off
	s_cbranch_vccnz .LBB0_1732
	v_cvt_pk_bf16_f32 v72, v60, v61
	v_mul_f32_e32 v61, v61, v61
	v_cvt_pk_bf16_f32 v73, v62, v63
	v_lshl_add_u64 v[70:71], v[70:71], 1, s[4:5]
	v_fmac_f32_e32 v61, v60, v60
	v_mul_f32_e32 v60, v63, v63
	global_store_dwordx2 v[70:71], v[72:73], off
	v_fmac_f32_e32 v60, v62, v62
	v_add_f32_e32 v74, v61, v60
	s_waitcnt vmcnt(4)
	v_mov_b64_e32 v[60:61], v[168:169]
	v_mov_b64_e32 v[62:63], v[170:171]
	v_pk_add_f32 v[62:63], v[58:59], v[62:63]
	v_pk_add_f32 v[60:61], v[56:57], v[60:61]
	global_store_dwordx4 v[66:67], v[60:63], off offset:64
	v_cvt_pk_bf16_f32 v72, v60, v61
	v_cvt_pk_bf16_f32 v73, v62, v63
	v_mul_f32_e32 v61, v61, v61
	v_fmac_f32_e32 v61, v60, v60
	v_mul_f32_e32 v60, v63, v63
	v_fmac_f32_e32 v60, v62, v62
	global_store_dwordx2 v[70:71], v[72:73], off offset:32
	v_add_f32_e32 v60, v61, v60
	v_add_f32_e32 v74, v74, v60
	s_waitcnt vmcnt(5)
	v_mov_b64_e32 v[60:61], v[172:173]
	v_mov_b64_e32 v[62:63], v[174:175]
	v_pk_add_f32 v[62:63], v[54:55], v[62:63]
	v_pk_add_f32 v[60:61], v[52:53], v[60:61]
	global_store_dwordx4 v[66:67], v[60:63], off offset:512
	v_cvt_pk_bf16_f32 v72, v60, v61
	v_cvt_pk_bf16_f32 v73, v62, v63
	v_mul_f32_e32 v61, v61, v61
	v_fmac_f32_e32 v61, v60, v60
	v_mul_f32_e32 v60, v63, v63
	v_fmac_f32_e32 v60, v62, v62
	global_store_dwordx2 v[70:71], v[72:73], off offset:256
	v_add_f32_e32 v60, v61, v60
	v_add_f32_e32 v74, v74, v60
	s_waitcnt vmcnt(6)
	v_mov_b64_e32 v[60:61], v[176:177]
	v_mov_b64_e32 v[62:63], v[178:179]
	v_pk_add_f32 v[62:63], v[50:51], v[62:63]
	v_pk_add_f32 v[60:61], v[48:49], v[60:61]
	global_store_dwordx4 v[66:67], v[60:63], off offset:576
	v_cvt_pk_bf16_f32 v72, v60, v61
	v_cvt_pk_bf16_f32 v73, v62, v63
	v_mul_f32_e32 v61, v61, v61
	v_fmac_f32_e32 v61, v60, v60
	v_mul_f32_e32 v60, v63, v63
	v_fmac_f32_e32 v60, v62, v62
	v_and_b32_e32 v62, 64, v197
	v_add_f32_e32 v60, v61, v60
	v_xor_b32_e32 v61, 16, v197
	v_add_u32_e32 v62, 64, v62
	v_cmp_lt_i32_e32 vcc, v61, v62
	v_add_f32_e32 v60, v74, v60
	global_store_dwordx2 v[70:71], v[72:73], off offset:288
	v_cndmask_b32_e32 v61, v197, v61, vcc
	v_lshlrev_b32_e32 v61, 2, v61
	ds_bpermute_b32 v61, v61, v60
	s_waitcnt lgkmcnt(0)
	v_add_f32_e32 v60, v60, v61
	v_xor_b32_e32 v61, 32, v197
	v_cmp_lt_i32_e32 vcc, v61, v62
	s_nop 1
	v_cndmask_b32_e32 v61, v197, v61, vcc
	v_lshlrev_b32_e32 v61, 2, v61
	ds_bpermute_b32 v61, v61, v60
	s_and_saveexec_b64 s[52:53], s[0:1]
	s_cbranch_execz .LBB0_1708
	v_lshlrev_b64 v[62:63], 6, v[68:69]
	v_readlane_b32 s26, v254, 43
	v_lshl_add_u64 v[62:63], s[30:31], 0, v[62:63]
	v_readlane_b32 s27, v254, 44
	v_lshl_add_u64 v[62:63], s[50:51], 2, v[62:63]
	s_mov_b32 s29, s27
	s_lshl_b32 s28, s65, 2
	v_writelane_b32 v254, s26, 43
	v_lshl_add_u64 v[62:63], v[62:63], 0, s[28:29]
	s_waitcnt lgkmcnt(0)
	v_add_f32_e32 v60, v60, v61
	v_writelane_b32 v254, s27, 44
	global_store_dword v[62:63], v60, off

.LBB0_1710:
	s_nop 1
	v_add_u32_e32 v50, 0x90, v138
	v_ashrrev_i32_e32 v51, 31, v50
	v_lshlrev_b64 v[48:49], 10, v[50:51]
	v_readlane_b32 s84, v254, 45
	v_lshl_add_u64 v[52:53], v[48:49], 0, v[136:137]
	v_readlane_b32 s90, v254, 51
	v_readlane_b32 s91, v254, 52
	s_and_b64 vcc, exec, s[38:39]
	v_readlane_b32 s85, v254, 46
	v_lshl_add_u64 v[48:49], v[52:53], 2, s[90:91]
	global_load_dwordx4 v[164:167], v[48:49], off
	global_load_dwordx4 v[168:171], v[48:49], off offset:64
	global_load_dwordx4 v[172:175], v[48:49], off offset:512
	global_load_dwordx4 v[176:179], v[48:49], off offset:576
	v_readlane_b32 s86, v254, 47
	v_readlane_b32 s87, v254, 48
	v_readlane_b32 s88, v254, 49
	v_readlane_b32 s89, v254, 50
	s_waitcnt vmcnt(3)
	v_mov_b64_e32 v[54:55], v[164:165]
	v_mov_b64_e32 v[56:57], v[166:167]
	v_pk_add_f32 v[46:47], v[46:47], v[56:57]
	v_pk_add_f32 v[44:45], v[44:45], v[54:55]
	global_store_dwordx4 v[48:49], v[44:47], off
	s_cbranch_vccnz .LBB0_1733
	v_cvt_pk_bf16_f32 v54, v44, v45
	v_mul_f32_e32 v45, v45, v45
	v_cvt_pk_bf16_f32 v55, v46, v47
	v_lshl_add_u64 v[52:53], v[52:53], 1, s[4:5]
	v_fmac_f32_e32 v45, v44, v44
	v_mul_f32_e32 v44, v47, v47
	global_store_dwordx2 v[52:53], v[54:55], off
	v_fmac_f32_e32 v44, v46, v46
	v_add_f32_e32 v56, v45, v44
	s_waitcnt vmcnt(4)
	v_mov_b64_e32 v[44:45], v[168:169]
	v_mov_b64_e32 v[46:47], v[170:171]
	v_pk_add_f32 v[46:47], v[42:43], v[46:47]
	v_pk_add_f32 v[44:45], v[40:41], v[44:45]
	global_store_dwordx4 v[48:49], v[44:47], off offset:64
	v_cvt_pk_bf16_f32 v54, v44, v45
	v_cvt_pk_bf16_f32 v55, v46, v47
	v_mul_f32_e32 v45, v45, v45
	v_fmac_f32_e32 v45, v44, v44
	v_mul_f32_e32 v44, v47, v47
	v_fmac_f32_e32 v44, v46, v46
	global_store_dwordx2 v[52:53], v[54:55], off offset:32
	v_add_f32_e32 v44, v45, v44
	v_add_f32_e32 v56, v56, v44
	s_waitcnt vmcnt(5)
	v_mov_b64_e32 v[44:45], v[172:173]
	v_mov_b64_e32 v[46:47], v[174:175]
	v_pk_add_f32 v[46:47], v[38:39], v[46:47]
	v_pk_add_f32 v[44:45], v[36:37], v[44:45]
	global_store_dwordx4 v[48:49], v[44:47], off offset:512
	v_cvt_pk_bf16_f32 v54, v44, v45
	v_cvt_pk_bf16_f32 v55, v46, v47
	v_mul_f32_e32 v45, v45, v45
	v_fmac_f32_e32 v45, v44, v44
	v_mul_f32_e32 v44, v47, v47
	v_fmac_f32_e32 v44, v46, v46
	global_store_dwordx2 v[52:53], v[54:55], off offset:256
	v_add_f32_e32 v44, v45, v44
	v_add_f32_e32 v56, v56, v44
	s_waitcnt vmcnt(6)
	v_mov_b64_e32 v[44:45], v[176:177]
	v_mov_b64_e32 v[46:47], v[178:179]
	v_pk_add_f32 v[46:47], v[34:35], v[46:47]
	v_pk_add_f32 v[44:45], v[32:33], v[44:45]
	global_store_dwordx4 v[48:49], v[44:47], off offset:576
	v_cvt_pk_bf16_f32 v54, v44, v45
	v_cvt_pk_bf16_f32 v55, v46, v47
	v_mul_f32_e32 v45, v45, v45
	v_fmac_f32_e32 v45, v44, v44
	v_mul_f32_e32 v44, v47, v47
	v_fmac_f32_e32 v44, v46, v46
	v_and_b32_e32 v46, 64, v197
	v_add_f32_e32 v44, v45, v44
	v_xor_b32_e32 v45, 16, v197
	v_add_u32_e32 v46, 64, v46
	v_cmp_lt_i32_e32 vcc, v45, v46
	v_add_f32_e32 v44, v56, v44
	global_store_dwordx2 v[52:53], v[54:55], off offset:288
	v_cndmask_b32_e32 v45, v197, v45, vcc
	v_lshlrev_b32_e32 v45, 2, v45
	ds_bpermute_b32 v45, v45, v44
	s_waitcnt lgkmcnt(0)
	v_add_f32_e32 v44, v44, v45
	v_xor_b32_e32 v45, 32, v197
	v_cmp_lt_i32_e32 vcc, v45, v46
	s_nop 1
	v_cndmask_b32_e32 v45, v197, v45, vcc
	v_lshlrev_b32_e32 v45, 2, v45
	ds_bpermute_b32 v45, v45, v44
	s_and_saveexec_b64 s[52:53], s[0:1]
	s_cbranch_execz .LBB0_1713
	v_lshlrev_b64 v[46:47], 6, v[50:51]
	v_readlane_b32 s26, v254, 43
	v_lshl_add_u64 v[46:47], s[30:31], 0, v[46:47]
	v_readlane_b32 s27, v254, 44
	v_lshl_add_u64 v[46:47], s[50:51], 2, v[46:47]
	s_mov_b32 s29, s27
	s_lshl_b32 s28, s65, 2
	v_writelane_b32 v254, s26, 43
	v_lshl_add_u64 v[46:47], v[46:47], 0, s[28:29]
	s_waitcnt lgkmcnt(0)
	v_add_f32_e32 v44, v44, v45
	v_writelane_b32 v254, s27, 44
	global_store_dword v[46:47], v44, off

.LBB0_1715:
	s_nop 1
	v_add_u32_e32 v34, 0xa0, v138
	v_ashrrev_i32_e32 v35, 31, v34
	v_lshlrev_b64 v[32:33], 10, v[34:35]
	v_readlane_b32 s84, v254, 45
	v_lshl_add_u64 v[36:37], v[32:33], 0, v[136:137]
	v_readlane_b32 s90, v254, 51
	v_readlane_b32 s91, v254, 52
	s_and_b64 vcc, exec, s[38:39]
	v_readlane_b32 s85, v254, 46
	v_lshl_add_u64 v[32:33], v[36:37], 2, s[90:91]
	global_load_dwordx4 v[164:167], v[32:33], off
	global_load_dwordx4 v[168:171], v[32:33], off offset:64
	global_load_dwordx4 v[172:175], v[32:33], off offset:512
	global_load_dwordx4 v[176:179], v[32:33], off offset:576
	v_readlane_b32 s86, v254, 47
	v_readlane_b32 s87, v254, 48
	v_readlane_b32 s88, v254, 49
	v_readlane_b32 s89, v254, 50
	s_waitcnt vmcnt(3)
	v_mov_b64_e32 v[38:39], v[164:165]
	v_mov_b64_e32 v[40:41], v[166:167]
	v_pk_add_f32 v[30:31], v[30:31], v[40:41]
	v_pk_add_f32 v[28:29], v[28:29], v[38:39]
	global_store_dwordx4 v[32:33], v[28:31], off
	s_cbranch_vccnz .LBB0_1734
	v_cvt_pk_bf16_f32 v38, v28, v29
	v_mul_f32_e32 v29, v29, v29
	v_cvt_pk_bf16_f32 v39, v30, v31
	v_lshl_add_u64 v[36:37], v[36:37], 1, s[4:5]
	v_fmac_f32_e32 v29, v28, v28
	v_mul_f32_e32 v28, v31, v31
	global_store_dwordx2 v[36:37], v[38:39], off
	v_fmac_f32_e32 v28, v30, v30
	v_add_f32_e32 v40, v29, v28
	s_waitcnt vmcnt(4)
	v_mov_b64_e32 v[28:29], v[168:169]
	v_mov_b64_e32 v[30:31], v[170:171]
	v_pk_add_f32 v[30:31], v[26:27], v[30:31]
	v_pk_add_f32 v[28:29], v[24:25], v[28:29]
	global_store_dwordx4 v[32:33], v[28:31], off offset:64
	v_cvt_pk_bf16_f32 v38, v28, v29
	v_cvt_pk_bf16_f32 v39, v30, v31
	v_mul_f32_e32 v29, v29, v29
	v_fmac_f32_e32 v29, v28, v28
	v_mul_f32_e32 v28, v31, v31
	v_fmac_f32_e32 v28, v30, v30
	global_store_dwordx2 v[36:37], v[38:39], off offset:32
	v_add_f32_e32 v28, v29, v28
	v_add_f32_e32 v40, v40, v28
	s_waitcnt vmcnt(5)
	v_mov_b64_e32 v[28:29], v[172:173]
	v_mov_b64_e32 v[30:31], v[174:175]
	v_pk_add_f32 v[30:31], v[22:23], v[30:31]
	v_pk_add_f32 v[28:29], v[20:21], v[28:29]
	global_store_dwordx4 v[32:33], v[28:31], off offset:512
	v_cvt_pk_bf16_f32 v38, v28, v29
	v_cvt_pk_bf16_f32 v39, v30, v31
	v_mul_f32_e32 v29, v29, v29
	v_fmac_f32_e32 v29, v28, v28
	v_mul_f32_e32 v28, v31, v31
	v_fmac_f32_e32 v28, v30, v30
	global_store_dwordx2 v[36:37], v[38:39], off offset:256
	v_add_f32_e32 v28, v29, v28
	v_add_f32_e32 v40, v40, v28
	s_waitcnt vmcnt(6)
	v_mov_b64_e32 v[28:29], v[176:177]
	v_mov_b64_e32 v[30:31], v[178:179]
	v_pk_add_f32 v[30:31], v[18:19], v[30:31]
	v_pk_add_f32 v[28:29], v[16:17], v[28:29]
	global_store_dwordx4 v[32:33], v[28:31], off offset:576
	v_cvt_pk_bf16_f32 v38, v28, v29
	v_cvt_pk_bf16_f32 v39, v30, v31
	v_mul_f32_e32 v29, v29, v29
	v_fmac_f32_e32 v29, v28, v28
	v_mul_f32_e32 v28, v31, v31
	v_fmac_f32_e32 v28, v30, v30
	v_and_b32_e32 v30, 64, v197
	v_add_f32_e32 v28, v29, v28
	v_xor_b32_e32 v29, 16, v197
	v_add_u32_e32 v30, 64, v30
	v_cmp_lt_i32_e32 vcc, v29, v30
	v_add_f32_e32 v28, v40, v28
	global_store_dwordx2 v[36:37], v[38:39], off offset:288
	v_cndmask_b32_e32 v29, v197, v29, vcc
	v_lshlrev_b32_e32 v29, 2, v29
	ds_bpermute_b32 v29, v29, v28
	s_waitcnt lgkmcnt(0)
	v_add_f32_e32 v28, v28, v29
	v_xor_b32_e32 v29, 32, v197
	v_cmp_lt_i32_e32 vcc, v29, v30
	s_nop 1
	v_cndmask_b32_e32 v29, v197, v29, vcc
	v_lshlrev_b32_e32 v29, 2, v29
	ds_bpermute_b32 v29, v29, v28
	s_and_saveexec_b64 s[52:53], s[0:1]
	s_cbranch_execz .LBB0_1718
	v_lshlrev_b64 v[30:31], 6, v[34:35]
	v_readlane_b32 s26, v254, 43
	v_lshl_add_u64 v[30:31], s[30:31], 0, v[30:31]
	v_readlane_b32 s27, v254, 44
	v_lshl_add_u64 v[30:31], s[50:51], 2, v[30:31]
	s_mov_b32 s29, s27
	s_lshl_b32 s28, s65, 2
	v_writelane_b32 v254, s26, 43
	v_lshl_add_u64 v[30:31], v[30:31], 0, s[28:29]
	s_waitcnt lgkmcnt(0)
	v_add_f32_e32 v28, v28, v29
	v_writelane_b32 v254, s27, 44
	global_store_dword v[30:31], v28, off

.LBB0_1720:
	s_nop 1
	v_add_u32_e32 v18, 0xb0, v138
	v_ashrrev_i32_e32 v19, 31, v18
	v_lshlrev_b64 v[16:17], 10, v[18:19]
	v_readlane_b32 s84, v254, 45
	v_lshl_add_u64 v[20:21], v[16:17], 0, v[136:137]
	v_readlane_b32 s90, v254, 51
	v_readlane_b32 s91, v254, 52
	s_and_b64 vcc, exec, s[38:39]
	v_readlane_b32 s85, v254, 46
	v_lshl_add_u64 v[16:17], v[20:21], 2, s[90:91]
	global_load_dwordx4 v[164:167], v[16:17], off
	global_load_dwordx4 v[168:171], v[16:17], off offset:64
	global_load_dwordx4 v[172:175], v[16:17], off offset:512
	global_load_dwordx4 v[176:179], v[16:17], off offset:576
	v_readlane_b32 s86, v254, 47
	v_readlane_b32 s87, v254, 48
	v_readlane_b32 s88, v254, 49
	v_readlane_b32 s89, v254, 50
	s_waitcnt vmcnt(3)
	v_mov_b64_e32 v[22:23], v[164:165]
	v_mov_b64_e32 v[24:25], v[166:167]
	v_pk_add_f32 v[14:15], v[14:15], v[24:25]
	v_pk_add_f32 v[12:13], v[12:13], v[22:23]
	global_store_dwordx4 v[16:17], v[12:15], off
	s_cbranch_vccnz .LBB0_1735
	v_cvt_pk_bf16_f32 v22, v12, v13
	v_mul_f32_e32 v13, v13, v13
	v_cvt_pk_bf16_f32 v23, v14, v15
	v_lshl_add_u64 v[20:21], v[20:21], 1, s[4:5]
	v_fmac_f32_e32 v13, v12, v12
	v_mul_f32_e32 v12, v15, v15
	global_store_dwordx2 v[20:21], v[22:23], off
	v_fmac_f32_e32 v12, v14, v14
	v_add_f32_e32 v24, v13, v12
	s_waitcnt vmcnt(4)
	v_mov_b64_e32 v[12:13], v[168:169]
	v_mov_b64_e32 v[14:15], v[170:171]
	v_pk_add_f32 v[14:15], v[10:11], v[14:15]
	v_pk_add_f32 v[12:13], v[8:9], v[12:13]
	global_store_dwordx4 v[16:17], v[12:15], off offset:64
	v_cvt_pk_bf16_f32 v22, v12, v13
	v_cvt_pk_bf16_f32 v23, v14, v15
	v_mul_f32_e32 v13, v13, v13
	v_fmac_f32_e32 v13, v12, v12
	v_mul_f32_e32 v12, v15, v15
	v_fmac_f32_e32 v12, v14, v14
	global_store_dwordx2 v[20:21], v[22:23], off offset:32
	v_add_f32_e32 v12, v13, v12
	v_add_f32_e32 v24, v24, v12
	s_waitcnt vmcnt(5)
	v_mov_b64_e32 v[12:13], v[172:173]
	v_mov_b64_e32 v[14:15], v[174:175]
	v_pk_add_f32 v[14:15], v[6:7], v[14:15]
	v_pk_add_f32 v[12:13], v[4:5], v[12:13]
	global_store_dwordx4 v[16:17], v[12:15], off offset:512
	v_cvt_pk_bf16_f32 v22, v12, v13
	v_cvt_pk_bf16_f32 v23, v14, v15
	v_mul_f32_e32 v13, v13, v13
	v_fmac_f32_e32 v13, v12, v12
	v_mul_f32_e32 v12, v15, v15
	v_fmac_f32_e32 v12, v14, v14
	global_store_dwordx2 v[20:21], v[22:23], off offset:256
	v_add_f32_e32 v12, v13, v12
	v_add_f32_e32 v24, v24, v12
	s_waitcnt vmcnt(6)
	v_mov_b64_e32 v[12:13], v[176:177]
	v_mov_b64_e32 v[14:15], v[178:179]
	v_pk_add_f32 v[14:15], v[2:3], v[14:15]
	v_pk_add_f32 v[12:13], v[0:1], v[12:13]
	global_store_dwordx4 v[16:17], v[12:15], off offset:576
	v_cvt_pk_bf16_f32 v22, v12, v13
	v_cvt_pk_bf16_f32 v23, v14, v15
	v_mul_f32_e32 v13, v13, v13
	v_fmac_f32_e32 v13, v12, v12
	v_mul_f32_e32 v12, v15, v15
	v_fmac_f32_e32 v12, v14, v14
	v_and_b32_e32 v14, 64, v197
	v_add_f32_e32 v12, v13, v12
	v_xor_b32_e32 v13, 16, v197
	v_add_u32_e32 v14, 64, v14
	v_cmp_lt_i32_e32 vcc, v13, v14
	v_add_f32_e32 v12, v24, v12
	global_store_dwordx2 v[20:21], v[22:23], off offset:288
	v_cndmask_b32_e32 v13, v197, v13, vcc
	v_lshlrev_b32_e32 v13, 2, v13
	ds_bpermute_b32 v13, v13, v12
	s_waitcnt lgkmcnt(0)
	v_add_f32_e32 v12, v12, v13
	v_xor_b32_e32 v13, 32, v197
	v_cmp_lt_i32_e32 vcc, v13, v14
	s_nop 1
	v_cndmask_b32_e32 v13, v197, v13, vcc
	v_lshlrev_b32_e32 v13, 2, v13
	ds_bpermute_b32 v13, v13, v12
	s_and_saveexec_b64 s[38:39], s[0:1]
	s_cbranch_execz .LBB0_1723
	v_lshlrev_b64 v[14:15], 6, v[18:19]
	v_readlane_b32 s26, v254, 43
	v_lshl_add_u64 v[14:15], s[30:31], 0, v[14:15]
	v_readlane_b32 s27, v254, 44
	v_lshl_add_u64 v[14:15], s[50:51], 2, v[14:15]
	s_mov_b32 s29, s27
	s_lshl_b32 s28, s65, 2
	v_writelane_b32 v254, s26, 43
	v_lshl_add_u64 v[14:15], v[14:15], 0, s[28:29]
	s_waitcnt lgkmcnt(0)
	v_add_f32_e32 v12, v12, v13
	v_writelane_b32 v254, s27, 44
	global_store_dword v[14:15], v12, off
